# E12 on E23: seam closing block skips the redundant XGEN reload when the waiting loop already saw the release
# speedup vs baseline: 1.0322x; 1.0007x over previous
.LBB0_75:
	s_or_b64 exec, exec, s[26:27]
	v_cmp_eq_u32_e32 vcc, -1, v2
	s_and_saveexec_b64 s[26:27], vcc
	v_mov_b32_e32 v4, 0x20048
	ds_read_b32 v3, v4
	s_waitcnt lgkmcnt(0)
	v_or_b32_e32 v3, 0x80000000, v3
	ds_write_b32 v4, v3
	s_or_b64 exec, exec, s[26:27]

.LBB0_257:
	s_and_saveexec_b64 s[4:5], s[38:39]
	v_readlane_b32 s16, v252, 60
	v_readlane_b32 s97, v252, 18
	v_readlane_b32 s14, v252, 2
	v_readlane_b32 s12, v252, 19
	s_mov_b64 s[90:91], s[92:93]
	v_readlane_b32 s17, v252, 61
	v_readlane_b32 s15, v252, 3
	s_cbranch_execz .LBB0_273
	s_add_i32 s2, 0, 0x20048
	v_mov_b32_e32 v1, s2
	ds_read_b32 v2, v1
	s_waitcnt lgkmcnt(0)
	v_cmp_eq_u32_e32 vcc, 0, v2
	s_cbranch_vccnz .LBB0_273
	v_cmp_gt_i32_e32 vcc, 0, v2
	v_mov_b32_e32 v1, 0
	s_cbranch_vccnz .LBB0_272
	v_mov_b32_e32 v1, 0
	global_load_dword v3, v1, s[66:67] sc1
	v_add_u32_e32 v2, -1, v2
	s_waitcnt vmcnt(0)
	v_cmp_ne_u32_e32 vcc, v3, v2
	s_cbranch_vccnz .LBB0_272
	s_mov_b32 s2, 1
	s_branch .LBB0_262

.LBB0_370:
	s_or_b64 exec, exec, s[18:19]
	v_cmp_eq_u32_e32 vcc, -1, v2
	s_and_saveexec_b64 s[18:19], vcc
	v_mov_b32_e32 v4, 0x20048
	ds_read_b32 v3, v4
	s_waitcnt lgkmcnt(0)
	v_or_b32_e32 v3, 0x80000000, v3
	ds_write_b32 v4, v3
	s_or_b64 exec, exec, s[18:19]

.LBB0_551:
	s_and_saveexec_b64 s[8:9], s[38:39]
	s_cbranch_execz .LBB0_567
	v_readlane_b32 s2, v252, 26
	s_nop 1
	v_mov_b32_e32 v2, s2
	ds_read_b32 v2, v2
	s_waitcnt lgkmcnt(0)
	v_cmp_eq_u32_e32 vcc, 0, v2
	s_cbranch_vccnz .LBB0_567
	v_cmp_gt_i32_e32 vcc, 0, v2
	s_cbranch_vccnz .LBB0_566
	v_readlane_b32 s12, v252, 34
	v_readlane_b32 s13, v252, 35
	v_add_u32_e32 v2, -1, v2
	s_nop 3
	global_load_dword v3, v147, s[12:13] sc1
	s_waitcnt vmcnt(0)
	v_cmp_ne_u32_e32 vcc, v3, v2
	s_cbranch_vccnz .LBB0_566
	s_mov_b32 s2, 1
	s_branch .LBB0_556

.LBB0_829:
	s_and_saveexec_b64 s[8:9], s[40:41]
	s_cbranch_execz .LBB0_845
	v_readlane_b32 s2, v252, 26
	s_nop 1
	v_mov_b32_e32 v2, s2
	ds_read_b32 v2, v2
	s_waitcnt lgkmcnt(0)
	v_cmp_eq_u32_e32 vcc, 0, v2
	s_cbranch_vccnz .LBB0_845
	v_cmp_gt_i32_e32 vcc, 0, v2
	s_cbranch_vccnz .LBB0_844
	v_readlane_b32 s12, v252, 34
	v_readlane_b32 s13, v252, 35
	v_add_u32_e32 v2, -1, v2
	s_nop 3
	global_load_dword v3, v147, s[12:13] sc1
	s_waitcnt vmcnt(0)
	v_cmp_ne_u32_e32 vcc, v3, v2
	s_cbranch_vccnz .LBB0_844
	s_mov_b32 s2, 1
	s_branch .LBB0_834

.LBB0_1152:
	s_and_saveexec_b64 s[8:9], s[42:43]
	s_cbranch_execz .LBB0_1168
	v_readlane_b32 s2, v252, 26
	s_nop 1
	v_mov_b32_e32 v2, s2
	ds_read_b32 v2, v2
	s_waitcnt lgkmcnt(0)
	v_cmp_eq_u32_e32 vcc, 0, v2
	s_cbranch_vccnz .LBB0_1168
	v_cmp_gt_i32_e32 vcc, 0, v2
	s_cbranch_vccnz .LBB0_1167
	v_readlane_b32 s12, v252, 34
	v_readlane_b32 s13, v252, 35
	v_add_u32_e32 v2, -1, v2
	s_nop 3
	global_load_dword v3, v147, s[12:13] sc1
	s_waitcnt vmcnt(0)
	v_cmp_ne_u32_e32 vcc, v3, v2
	s_cbranch_vccnz .LBB0_1167
	s_mov_b32 s2, 1
	s_branch .LBB0_1157
